# attention tile loop back-edge rotation: next tile's K/V DMA address arithmetic moved in front of the tile-end barrier, only the four issues stay behind it
# baseline (speedup 1.0000x reference)
; __device__ __forceinline__ void attn_block(const bf16_t* __restrict__ proj, bf16_t* __restrict__ mixed, int b, int h, int qb, char* lds) {
;     ...
;     for (int t = 0; t < NT; ++t) {
;         const int buf = t & 1, kb = t * 64;
;         if (t + 1 < NT) FA_DMA(kb + 64, buf ^ 1);
;     ...
;         asm volatile("s_waitcnt vmcnt(0)" ::: "memory");
;         __syncthreads();
.LBB0_339:
	s_waitcnt vmcnt(0)
	s_add_u32 s94, s94, 0xe0000
	s_addc_u32 s95, s95, 0
	s_add_i32 s86, s86, 1
	s_sub_i32 s65, s65, 64
	s_add_i32 s89, s89, 64
	s_add_i32 s57, s86, -1
	s_and_b32 s57, s57, 1
	s_lshl_b32 s57, s57, 14
	s_xor_b32 s57, s57, 0x4000
	s_add_i32 s57, s87, s57
	v_lshl_add_u64 v[116:117], v[180:181], 0, s[94:95]
	v_lshl_add_u64 v[118:119], v[178:179], 0, s[94:95]
	s_mov_b64 s[96:97], 0xa950800
	s_nop 0
	v_lshl_add_u64 v[120:121], v[116:117], 0, s[96:97]
	s_mov_b64 s[96:97], 0xa951000
	s_nop 0
	v_lshl_add_u64 v[122:123], v[118:119], 0, s[96:97]
	s_mov_b64 s[96:97], 0xa8e0800
	s_nop 0
	v_lshl_add_u64 v[116:117], v[116:117], 0, s[96:97]
	s_mov_b64 s[96:97], 0xa8e1000
	s_nop 0
	v_lshl_add_u64 v[118:119], v[118:119], 0, s[96:97]
	s_cmp_eq_u32 s79, s94
	s_waitcnt vmcnt(0) lgkmcnt(0)
	s_barrier
	s_cbranch_scc1 .LBB0_341
	v_mov_b32_e32 v233, v15
	v_mov_b32_e32 v234, v14
	s_add_i32 s56, s86, -1
	s_and_b32 s56, s56, 1
	s_cmp_ge_u32 s86, s88
	s_cbranch_scc0 .Lattn_dma_fast
	s_branch .LBB0_312
.Lattn_dma_fast:
	s_add_i32 m0, s57, 0x8000
	s_nop 0
	global_load_lds_dwordx4 v[116:117], off
	s_mov_b32 m0, s57
	s_nop 0
	global_load_lds_dwordx4 v[118:119], off
	s_add_i32 m0, s57, 0xa000
	s_nop 0
	global_load_lds_dwordx4 v[120:121], off
	s_add_i32 m0, s57, 0x2000
	s_nop 0
	global_load_lds_dwordx4 v[122:123], off
	s_branch .LBB0_312
